# grid-size guards: idle-tail conversion windows, reduced P1 item set and the P11 item rotation apply only to a 256-workgroup grid (other grids fall back to the original mapping)
# speedup vs baseline: 1.0030x; 1.0005x over previous
; #define INP(k) karg_in(k)
; #define lane opq(lane_now())
; __global__ void __launch_bounds__(NTHR, 2) fwd_megakernel(Params P) {
;     ...
;     { pg8::Gemm g{(const bf16*)(ws + WS_CB), (const bf16*)(ws + WS_WADA), nullptr, nullptr, D}; pg8::StaticOrder S; S.init(256, NADA, G, wg);
;       EpiAda E{ADA, INP(9)}; pg8::gemm_phase(lds, g, S, E, wave);
;       if (wg >= 36) prologue<1>(P, lds, (wg - 36) * NWAVES + wave, (G - 36) * NWAVES, wave, lane); }
.LBB0_220:
	s_mov_b32 s99, 0
	s_cmpk_eq_u32 s78, 0x100
	s_cbranch_scc1 .Lcv_modeok
	s_mov_b32 s99, 4
.Lcv_modeok:
	s_cmp_lt_i32 s2, 36
	s_cbranch_scc1 .LBB0_345

; template <int PART>
; __device__ __forceinline__ void prologue(const Params& P, LAS unsigned char* lds, int gw, int NGW, int wave, int lane) {
;     ...
;     for (int it = gw; it < NITEMS; it += NGW) {
;         int r = it;
;         if (PART == 0) { if (r >= I_ADA) break; r += I_FIRST; } else { if (r >= NITEMS - I_ADA) break; if (r >= I_FIRST) r += I_ADA; }
.LBB0_224:
	s_mov_b32 s12, 2
	s_cmp_eq_u32 s99, 4
	s_cbranch_scc0 .Lcv_split
	s_cmpk_gt_i32 s26, 0x378f
	s_cbranch_scc1 .LBB0_319
	s_add_i32 s22, s26, 0x1200
	s_cmpk_gt_i32 s26, 0x370f
	s_cbranch_scc1 .Lcv_go
	s_mov_b32 s22, s26
	s_branch .Lcv_go
.Lcv_split:
	s_cmp_eq_u32 s99, 0
	s_cbranch_scc0 .Lcv_tailmap
	s_cmpk_gt_i32 s26, 0x107f
	s_cbranch_scc1 .LBB0_319
	s_mov_b32 s22, s26
	s_cmpk_lt_i32 s26, 0xb00
	s_cbranch_scc1 .Lcv_go
	s_add_i32 s22, s26, 0xb00
	s_branch .Lcv_go

; __global__ void __launch_bounds__(NTHR, 2) fwd_megakernel(Params P) {
;     ...
;     { pg8::Gemm g{H, (const bf16*)(ws + WS_WUP1), nullptr, nullptr, D}; pg8::StaticOrder S; S.init(MPAD, 2 * FF, G, wg);
;       EpiSwiglu E{ACT}; pg8::gemm_phase(lds, g, S, E, wave); }
.LBB0_498:
	s_cmpk_lg_u32 s78, 0x100
	s_cbranch_scc1 .Lcv_skip3
	s_cmpk_lt_u32 s2, 0x96
	s_cbranch_scc1 .Lcv_skip3
	s_mov_b32 s99, 2
	s_sub_i32 s72, s2, 0x96
	s_lshl_b32 s72, s72, 3
	s_add_i32 s72, s72, s3
	s_addk_i32 s72, 0x120
	s_movk_i32 s12, 0x470
	s_branch .Lcv_pre

; __device__ __forceinline__ float* karg_out() { return *(volatile KAS fptr_t*)((const KAS char*)__builtin_amdgcn_kernarg_segment_ptr() + 256); }
; __global__ void __launch_bounds__(NTHR, 2) fwd_megakernel(Params P) {
;     ...
;     { pg8::Gemm g{H, (const bf16*)(ws + WS_WIN), nullptr, nullptr, D}; pg8::StaticOrder S; S.init(MPAD, NIN, G, wg);
;       EpiIn E{Z, MG, (float*)(ws + WS_ABL), karg_out()}; pg8::gemm_phase(lds, g, S, E, wave); }
.LBB0_970:
	s_cmpk_lg_u32 s78, 0x100
	s_cbranch_scc1 .Lcv_skip
	s_cmpk_lt_u32 s2, 0x61
	s_cbranch_scc1 .Lcv_skip
	s_mov_b32 s99, 1
	s_sub_i32 s72, s2, 0x61
	s_lshl_b32 s72, s72, 3
	s_add_i32 s72, s72, s3
	s_addk_i32 s72, 0x120
	s_movk_i32 s12, 0x618
	s_branch .Lcv_pre

; #define tid opq((wave << 6) | lane_now())
; __global__ void __launch_bounds__(NTHR, 2) fwd_megakernel(Params P) {
;     ...
;         for (int item = (G == 256 ? SS_TAIL : 0) + wg; item < NS * NH; item += G) delta_sample_item<1>(P, lds, item, tid);
.LBB0_2103:
	v_readlane_b32 s4, v238, 18
	v_readlane_b32 s5, v238, 19
	s_and_b64 s[4:5], exec, s[4:5]
	s_cselect_b32 s4, 0x212, 0
	s_mov_b32 s3, s2
	s_cmpk_lg_u32 s78, 0x100
	s_cbranch_scc1 .Lp11_norot
	s_add_i32 s3, s2, 0xf0
	s_and_b32 s3, s3, 0xff
.Lp11_norot:
	s_add_i32 s3, s4, s3
	s_cmpk_gt_i32 s3, 0x3ff
	s_mov_b32 s7, 0
	s_cbranch_scc1 .LBB0_2125
	s_mov_b32 s5, 0
	s_mov_b32 s4, s3
	s_lshl_b64 s[4:5], s[4:5], 16
	s_waitcnt lgkmcnt(0)
	s_add_u32 s12, s4, 0x46ebe00
	s_addc_u32 s13, s5, 0
	s_ashr_i32 s5, s78, 31
	s_mov_b32 s4, s78
	s_lshl_b64 s[14:15], s[4:5], 16
	s_movk_i32 s20, 0x180
	s_mov_b32 s21, 0x2040000
	v_mov_b32_e32 v1, 0
	s_mov_b32 s22, 0x90c0000
	s_mov_b32 s23, 0x9000
	s_movk_i32 s24, 0x3000
	s_movk_i32 s25, 0x6000
	s_mov_b32 s26, 0xfb915000
	s_mov_b32 s27, 0xfb916000
	s_mov_b32 s28, 0xfb917000
	s_mov_b32 s29, 0xfb918000
	v_mov_b32_e32 v12, 0x2e00000
	s_mov_b32 s30, 0x41a00000
	s_mov_b32 s31, 0x3f2aaaab
	v_mov_b32_e32 v13, 0x3ecc95a3
	s_mov_b32 s34, 0x3f317218
	s_mov_b32 s35, 0x7f800000
	s_mov_b32 s36, 0x33800000
	s_movk_i32 s37, 0xd000
	s_movk_i32 s38, 0xe000
	s_movk_i32 s39, 0xf000
	v_mov_b32_e32 v14, 0x300
	v_mov_b32_e32 v2, 0x3f317218
	v_mov_b32_e32 v15, 0x7f800000
	v_mov_b32_e32 v16, 0x7fc00000
	v_mov_b32_e32 v17, 0xff800000
	s_branch .LBB0_2106
